# redundant second s_barrier before the GLA state publish removed
# speedup vs baseline: 1.0034x; 1.0001x over previous
; #define LAS __attribute__((address_space(3)))
; template <bool FULL>
; __device__ __forceinline__ void gla_pass(const Params& P, LAS unsigned char* lds, f32x4 (&S)[8][2], int bh, int c0, int L, bool dry) {
;     ...
;         for (int kt = 0; kt < 8; ++kt) { const f32x4 dv = *(const LAS f32x4*)(Ldec + 16 * kt + 4 * g); S[kt][0] = S[kt][0] * dv; S[kt][1] = S[kt][1] * dv; }
; #pragma unroll
;         for (int k2 = 0; k2 < 2; ++k2)
; #pragma unroll
;             for (int kt = 0; kt < 8; ++kt) { const bf16x8 ak = trfrag(Lks, KS_P, 32 * k2, 32 * kt, g, fr);
;                 S[kt][0] = __builtin_amdgcn_mfma_f32_16x16x32_bf16(ak, vf[0][k2], S[kt][0], 0, 0, 0); S[kt][1] = __builtin_amdgcn_mfma_f32_16x16x32_bf16(ak, vf[1][k2], S[kt][1], 0, 0, 0); }
.LBB0_668:
	v_add_u32_e32 v100, 0x25000, v121
	s_waitcnt vmcnt(3)
	ds_read_b128 v[32:35], v100
	ds_read_b64_tr_b16 v[30:31], v116 offset:38016
	ds_read_b64_tr_b16 v[28:29], v116 offset:35840
	ds_read_b64_tr_b16 v[22:23], v116 offset:38048
	ds_read_b64_tr_b16 v[20:21], v116 offset:35872
	s_waitcnt vmcnt(2)
	ds_read_b128 v[40:43], v100 offset:64
	s_waitcnt vmcnt(0)
	ds_read_b64_tr_b16 v[50:51], v115 offset:1152
	ds_read_b64_tr_b16 v[48:49], v115
	s_waitcnt lgkmcnt(7)
	v_pk_mul_f32 v[46:47], v[90:91], v[34:35]
	v_pk_mul_f32 v[44:45], v[88:89], v[32:33]
	v_pk_mul_f32 v[34:35], v[86:87], v[34:35]
	ds_read_b64_tr_b16 v[52:53], v115 offset:32
	ds_read_b64_tr_b16 v[86:87], v115 offset:64
	ds_read_b64_tr_b16 v[90:91], v115 offset:96
	ds_read_b64_tr_b16 v[54:55], v115 offset:1184
	ds_read_b64_tr_b16 v[88:89], v115 offset:1216
	ds_read_b64_tr_b16 v[92:93], v115 offset:1248
	v_pk_mul_f32 v[32:33], v[84:85], v[32:33]
	s_waitcnt lgkmcnt(6)
	v_mfma_f32_16x16x32_bf16 v[44:47], v[48:51], v[28:31], v[44:47]
	v_mul_f32_e64 v82, v82, v42
	v_mul_f32_e64 v83, v83, v43
	v_pk_mul_f32 v[80:81], v[80:81], v[40:41]
	v_pk_mul_f32 v[42:43], v[78:79], v[42:43]
	v_mfma_f32_16x16x32_bf16 v[32:35], v[48:51], v[20:23], v[32:35]
	ds_read_b128 v[48:51], v100 offset:128
	v_pk_mul_f32 v[40:41], v[76:77], v[40:41]
	s_mul_i32 s4, s1, 3
	s_waitcnt lgkmcnt(3)
	v_mfma_f32_16x16x32_bf16 v[76:79], v[52:55], v[28:31], v[80:83]
	s_add_i32 s4, s4, s3
	s_lshl_b32 s4, s4, 17
	s_add_u32 s4, s18, s4
	ds_read_b128 v[80:83], v100 offset:192
	s_waitcnt lgkmcnt(1)
	v_pk_mul_f32 v[74:75], v[74:75], v[50:51]
	v_pk_mul_f32 v[72:73], v[72:73], v[48:49]
	v_mfma_f32_16x16x32_bf16 v[40:43], v[52:55], v[20:23], v[40:43]
	v_mul_f32_e64 v50, v70, v50
	v_mul_f32_e64 v51, v71, v51
	v_pk_mul_f32 v[48:49], v[68:69], v[48:49]
	s_waitcnt lgkmcnt(0)
	v_pk_mul_f32 v[54:55], v[66:67], v[82:83]
	v_mfma_f32_16x16x32_bf16 v[66:69], v[86:89], v[28:31], v[72:75]
	v_mul_f32_e64 v52, v64, v80
	v_mul_f32_e64 v53, v65, v81
	v_pk_mul_f32 v[58:59], v[58:59], v[82:83]
	v_pk_mul_f32 v[56:57], v[56:57], v[80:81]
	ds_read_b128 v[70:73], v100 offset:256
	ds_read_b128 v[80:83], v100 offset:320
	v_mfma_f32_16x16x32_bf16 v[48:51], v[86:89], v[20:23], v[48:51]
	ds_read_b64_tr_b16 v[84:85], v115 offset:128
	ds_read_b64_tr_b16 v[86:87], v115 offset:1280
	s_addc_u32 s5, s19, 0
	s_waitcnt lgkmcnt(3)
	v_pk_mul_f32 v[62:63], v[62:63], v[72:73]
	v_mfma_f32_16x16x32_bf16 v[52:55], v[90:93], v[28:31], v[52:55]
	v_mul_f32_e64 v60, v60, v70
	v_mul_f32_e64 v61, v61, v71
	v_pk_mul_f32 v[38:39], v[38:39], v[72:73]
	v_pk_mul_f32 v[36:37], v[36:37], v[70:71]
	v_mfma_f32_16x16x32_bf16 v[56:59], v[90:93], v[20:23], v[56:59]
	ds_read_b64_tr_b16 v[88:89], v115 offset:160
	ds_read_b64_tr_b16 v[92:93], v115 offset:192
	ds_read_b64_tr_b16 v[96:97], v115 offset:224
	ds_read_b64_tr_b16 v[90:91], v115 offset:1312
	ds_read_b64_tr_b16 v[94:95], v115 offset:1344
	ds_read_b64_tr_b16 v[98:99], v115 offset:1376
	s_waitcnt lgkmcnt(8)
	v_pk_mul_f32 v[26:27], v[26:27], v[82:83]
	v_pk_mul_f32 v[24:25], v[24:25], v[80:81]
	ds_read_b128 v[70:73], v100 offset:384
	v_pk_mul_f32 v[18:19], v[18:19], v[82:83]
	v_pk_mul_f32 v[16:17], v[16:17], v[80:81]
	ds_read_b128 v[80:83], v100 offset:448
	s_waitcnt lgkmcnt(8)
	v_mfma_f32_16x16x32_bf16 v[60:63], v[84:87], v[28:31], v[60:63]
	s_waitcnt lgkmcnt(1)
	v_pk_mul_f32 v[14:15], v[14:15], v[72:73]
	v_pk_mul_f32 v[12:13], v[12:13], v[70:71]
	v_pk_mul_f32 v[10:11], v[10:11], v[72:73]
	s_waitcnt lgkmcnt(0)
	v_pk_mul_f32 v[6:7], v[6:7], v[82:83]
	v_pk_mul_f32 v[4:5], v[4:5], v[80:81]
	v_mfma_f32_16x16x32_bf16 v[36:39], v[84:87], v[20:23], v[36:39]
	v_mul_f32_e64 v8, v8, v70
	v_mul_f32_e64 v9, v9, v71
	v_pk_mul_f32 v[2:3], v[2:3], v[82:83]
	v_pk_mul_f32 v[0:1], v[0:1], v[80:81]
	v_mfma_f32_16x16x32_bf16 v[24:27], v[88:91], v[28:31], v[24:27]
	s_mov_b32 s9, 0
	v_cmp_gt_i32_e32 vcc, 32, v114
	v_mfma_f32_16x16x32_bf16 v[16:19], v[88:91], v[20:23], v[16:19]
	ds_read_b64_tr_b16 v[84:85], v116 offset:53248
	ds_read_b64_tr_b16 v[86:87], v116 offset:55424
	ds_read_b64_tr_b16 v[90:91], v116 offset:55456
	ds_read_b64_tr_b16 v[88:89], v116 offset:53280
	v_mfma_f32_16x16x32_bf16 v[12:15], v[92:95], v[28:31], v[12:15]
	v_mfma_f32_16x16x32_bf16 v[4:7], v[96:99], v[28:31], v[4:7]
	ds_read_b64_tr_b16 v[28:29], v115 offset:9216
	ds_read_b64_tr_b16 v[30:31], v115 offset:10368
	v_mfma_f32_16x16x32_bf16 v[8:11], v[92:95], v[20:23], v[8:11]
	v_mfma_f32_16x16x32_bf16 v[0:3], v[96:99], v[20:23], v[0:3]
	ds_read_b64_tr_b16 v[20:21], v115 offset:9248
	ds_read_b64_tr_b16 v[70:71], v115 offset:9280
	ds_read_b64_tr_b16 v[80:81], v115 offset:9312
	ds_read_b64_tr_b16 v[22:23], v115 offset:10400
	ds_read_b64_tr_b16 v[72:73], v115 offset:10432
	ds_read_b64_tr_b16 v[82:83], v115 offset:10464
	s_waitcnt lgkmcnt(6)
	v_mfma_f32_16x16x32_bf16 v[44:47], v[28:31], v[84:87], v[44:47]
	v_mfma_f32_16x16x32_bf16 v[28:31], v[28:31], v[88:91], v[32:35]
	s_waitcnt lgkmcnt(2)
	v_mfma_f32_16x16x32_bf16 v[32:35], v[20:23], v[84:87], v[76:79]
	v_mfma_f32_16x16x32_bf16 v[20:23], v[20:23], v[88:91], v[40:43]
	s_waitcnt lgkmcnt(1)
	v_mfma_f32_16x16x32_bf16 v[40:43], v[70:73], v[84:87], v[66:69]
	ds_read_b64_tr_b16 v[64:65], v115 offset:9344
	s_nop 1
	ds_read_b64_tr_b16 v[66:67], v115 offset:10496
	s_waitcnt lgkmcnt(0)
	v_mfma_f32_16x16x32_bf16 v[60:63], v[64:67], v[84:87], v[60:63]
	v_mfma_f32_16x16x32_bf16 v[36:39], v[64:67], v[88:91], v[36:39]
	v_lshlrev_b32_e32 v64, 4, v114
	v_mfma_f32_16x16x32_bf16 v[48:51], v[70:73], v[88:91], v[48:51]
	ds_read_b64_tr_b16 v[68:69], v115 offset:9376
	ds_read_b64_tr_b16 v[72:73], v115 offset:9408
	ds_read_b64_tr_b16 v[76:77], v115 offset:9440
	ds_read_b64_tr_b16 v[70:71], v115 offset:10528
	ds_read_b64_tr_b16 v[74:75], v115 offset:10560
	ds_read_b64_tr_b16 v[78:79], v115 offset:10592
	s_waitcnt lgkmcnt(0)
	s_barrier
; __device__ __forceinline__ void gla_scan(const Params& P, LAS unsigned char* lds, int bh, int seg, int nseg, bool dry) {
;     ...
;         if (tid < 32) {
;             f32x4 dc = (f32x4){1.f, 1.f, 1.f, 1.f};
;             for (int n = c0; n < c0 + L; ++n) dc = dc * *(const f32x4*)(DEC + (size_t)(bh * 64 + n) * 128 + 4 * tid);
	s_and_saveexec_b64 s[10:11], vcc
	s_cbranch_execz .Lpub_nold
	v_lshlrev_b32_e32 v180, 2, v114
	v_ashrrev_i32_e32 v181, 31, v180
	s_or_b32 s8, s0, s22
	v_lshlrev_b64 v[184:185], 2, v[180:181]
	s_lshl_b32 s8, s8, 9
	s_mov_b32 s12, 0x1000
	v_lshl_add_u64 v[180:181], s[50:51], 0, v[184:185]
	s_mov_b32 s13, 0
	v_lshl_add_u64 v[180:181], v[180:181], 0, s[8:9]
	s_nop 0
	v_lshl_add_u64 v[182:183], v[180:181], 0, s[12:13]
	global_load_dwordx4 v[116:119], v[180:181], off
	global_load_dwordx4 v[120:123], v[180:181], off offset:512
	global_load_dwordx4 v[124:127], v[180:181], off offset:1024
	global_load_dwordx4 v[128:131], v[180:181], off offset:1536
	global_load_dwordx4 v[132:135], v[180:181], off offset:2048
	global_load_dwordx4 v[136:139], v[180:181], off offset:2560
	global_load_dwordx4 v[140:143], v[180:181], off offset:3072
	global_load_dwordx4 v[144:147], v[180:181], off offset:3584
	global_load_dwordx4 v[148:151], v[182:183], off
	global_load_dwordx4 v[152:155], v[182:183], off offset:512
	global_load_dwordx4 v[156:159], v[182:183], off offset:1024
	global_load_dwordx4 v[160:163], v[182:183], off offset:1536
	global_load_dwordx4 v[164:167], v[182:183], off offset:2048
	global_load_dwordx4 v[168:171], v[182:183], off offset:2560
	global_load_dwordx4 v[172:175], v[182:183], off offset:3072
	global_load_dwordx4 v[176:179], v[182:183], off offset:3584
